# attention staging wait counts the previous item's 9 stores exactly (no wait on store acks)
# baseline (speedup 1.0000x reference)
.Lpf_wait_cnt:
	s_cmp_eq_u32 s72, 7
	s_cbranch_scc1 .Lpf_wait8
	s_waitcnt vmcnt(9)
	s_branch .Lpf_wait_done

.Lpf_wait_done:
	ds_write_b128 v244, v[154:157]
	ds_write_b128 v245, v[158:161]
	ds_write_b128 v244, v[162:165] offset:8704
	ds_write_b128 v245, v[166:169] offset:9216
	ds_write_b128 v244, v[170:173] offset:17408
	ds_write_b128 v245, v[174:177] offset:18432
	ds_write_b128 v244, v[178:181] offset:26112
	ds_write_b128 v245, v[182:185] offset:27648
	ds_write_b128 v244, v[186:189] offset:34816
	ds_write_b128 v245, v[190:193] offset:36864
	ds_write_b128 v244, v[194:197] offset:43520
	ds_write_b128 v245, v[198:201] offset:46080
	ds_write_b128 v244, v[202:205] offset:52224
	ds_write_b128 v245, v[206:209] offset:55296
	ds_write_b128 v244, v[210:213] offset:60928
	ds_write_b128 v245, v[214:217] offset:64512
	s_waitcnt lgkmcnt(0)
	s_barrier
	s_and_b32 s8, s2, 2
	v_readlane_b32 s9, v252, 56
	s_or_b32 s74, s8, s9
	v_mov_b32_e32 v99, v218
	s_lshl_b32 s8, s74, 7
	v_readlane_b32 s9, v252, 55
	s_or_b32 s8, s9, s8
	v_readfirstlane_b32 s76, v99
	v_readlane_b32 s9, v253, 22
	s_ashr_i32 s73, s76, 6
	s_or_b32 s75, s8, s9
	v_and_b32_e32 v98, 63, v99
	s_cmp_gt_u32 s72, 1
	s_mov_b64 s[10:11], -1
	s_cbranch_scc0 .LBB0_1352
	s_cmp_gt_u32 s72, 3
	s_cbranch_scc0 .LBB0_1314
	s_lshl_b32 s77, s75, 7
	s_and_b32 s12, s77, 0x180
	v_ashrrev_i32_e32 v104, 4, v99
	s_movk_i32 s9, 0x120
	s_cmp_gt_u32 s72, 5
	v_mul_lo_u32 v102, v104, s33
	v_mul_lo_u32 v103, v104, s9
	s_cbranch_scc0 .LBB0_1276
	s_lshl_b32 s10, s8, 5
	s_lshl_b32 s28, s12, 1
	s_add_u32 s8, s66, s28
	v_lshl_add_u32 v0, s74, 8, v104
	v_lshlrev_b32_e32 v1, 4, v99
	s_addc_u32 s9, s67, 0
	v_and_b32_e32 v32, 0xf0, v1
	v_ashrrev_i32_e32 v1, 31, v0
	v_lshl_add_u64 v[2:3], s[8:9], 0, v[32:33]
	v_lshlrev_b64 v[0:1], 13, v[0:1]
	v_lshl_add_u64 v[0:1], v[2:3], 0, v[0:1]
	s_mov_b64 s[8:9], 0x40000
	v_lshl_add_u64 v[2:3], v[0:1], 0, s[8:9]
	s_mov_b32 s8, 0x40000
	v_add_co_u32_e32 v12, vcc, s8, v0
	s_mov_b64 s[8:9], 0x80000
	s_nop 0
	v_addc_co_u32_e32 v13, vcc, 0, v1, vcc
	s_nop 0
	s_nop 0
	v_lshl_add_u64 v[2:3], v[0:1], 0, s[8:9]
	s_mov_b32 s8, 0x80000
	v_add_co_u32_e32 v20, vcc, s8, v0
	s_mov_b64 s[8:9], 0xc0000
	s_nop 0
	v_addc_co_u32_e32 v21, vcc, 0, v1, vcc
	s_nop 0
	v_lshl_add_u64 v[2:3], v[0:1], 0, s[8:9]
	s_mov_b32 s8, 0xc0000
	v_add_co_u32_e32 v28, vcc, s8, v0
	s_mov_b64 s[8:9], 0x100000
	s_nop 0
	v_addc_co_u32_e32 v29, vcc, 0, v1, vcc
	v_add_co_u32_e32 v38, vcc, s79, v0
	s_nop 0
	v_lshl_add_u64 v[2:3], v[0:1], 0, s[8:9]
	v_addc_co_u32_e32 v39, vcc, 0, v1, vcc
	s_mov_b64 s[8:9], 0x140000
	s_nop 0
	v_lshl_add_u64 v[2:3], v[0:1], 0, s[8:9]
	s_mov_b32 s8, 0x140000
	v_add_co_u32_e32 v46, vcc, s8, v0
	s_mov_b64 s[8:9], 0x180000
	s_nop 0
	v_addc_co_u32_e32 v47, vcc, 0, v1, vcc
	s_nop 0
	v_lshl_add_u64 v[2:3], v[0:1], 0, s[8:9]
	s_mov_b32 s8, 0x180000
	v_add_co_u32_e32 v54, vcc, s8, v0
	s_mov_b64 s[8:9], 0x1c0000
	s_nop 0
	v_addc_co_u32_e32 v55, vcc, 0, v1, vcc
	s_nop 0
	v_lshl_add_u64 v[2:3], v[0:1], 0, s[8:9]
	s_mov_b32 s8, 0x1c0000
	v_add_co_u32_e32 v0, vcc, s8, v0
	s_and_b32 s10, s10, 0x3f80
	s_nop 0
	v_addc_co_u32_e32 v1, vcc, 0, v1, vcc
	v_readlane_b32 s8, v252, 31
	s_add_u32 s8, s8, s28
	v_readlane_b32 s9, v252, 32
	s_addc_u32 s9, s9, 0
	s_lshl_b32 s11, s73, 4
	v_and_b32_e32 v108, 15, v99
	s_add_i32 s11, s11, s10
	v_or_b32_e32 v82, s11, v108
	v_mov_b64_e32 v[0:1], s[8:9]
	v_mad_i64_i32 v[0:1], s[8:9], v82, s70, v[0:1]
	v_and_b32_e32 v106, 48, v99
	v_mov_b32_e32 v107, v33
	v_lshl_add_u64 v[70:71], v[0:1], 0, v[106:107]
	v_add3_u32 v83, 0, v32, v102
	s_nop 0
	v_lshrrev_b32_e32 v105, 2, v98
	v_add3_u32 v4, s27, v32, v103
	v_lshrrev_b32_e32 v6, 1, v98
	v_and_b32_e32 v32, 24, v6
	v_mov_b64_e32 v[4:5], s[24:25]
	v_mad_i64_i32 v[4:5], s[8:9], v82, s70, v[4:5]
	v_lshl_add_u64 v[4:5], v[4:5], 0, s[28:29]
	v_lshl_add_u64 v[4:5], v[4:5], 0, v[32:33]
	s_mov_b64 s[8:9], 0x11103000
	v_lshl_add_u64 v[78:79], v[4:5], 0, s[8:9]
	s_mov_b32 s8, 0x11103000
	v_add_co_u32_e32 v94, vcc, s8, v4
	s_waitcnt lgkmcnt(0)
	s_nop 0
	v_addc_co_u32_e32 v95, vcc, 0, v5, vcc
	v_mov_b64_e32 v[0:1], v[228:229]
	v_mov_b64_e32 v[2:3], v[230:231]
	v_mov_b64_e32 v[62:63], v[232:233]
	v_mov_b64_e32 v[64:65], v[234:235]
	v_mov_b64_e32 v[66:67], v[236:237]
	v_mov_b64_e32 v[68:69], v[238:239]
	v_mov_b64_e32 v[70:71], v[240:241]
	v_mov_b64_e32 v[72:73], v[242:243]
	s_add_u32 s48, s72, 1
	s_cmp_lt_u32 s48, 8
	s_cbranch_scc1 .Lpf_issue
